# phase mixing in P3: workgroups with bit 3 of their id set run attention before the FFT long conv, the others keep FFT first, so MFMA-heavy and VALU/LDS-heavy work overlap across the chip
# speedup vs baseline: 1.0037x; 1.0037x over previous
.LBB0_678:
	s_or_b64 exec, exec, s[40:41]
	s_bitcmp1_b32 s93, 3
	s_cbranch_scc0 .Lp3_fft_entry
	v_mov_b32_e32 v199, 1
	s_branch .LBB0_722
.Lp3_fft_entry:
	s_mov_b64 s[4:5], s[96:97]
	s_waitcnt lgkmcnt(0)
	s_barrier
	s_load_dwordx2 s[2:3], s[4:5], 0x60
	s_load_dwordx4 s[44:47], s[4:5], 0xc0
	s_mov_b32 s42, s93
	s_mov_b32 s18, s94
	v_mov_b32_e32 v168, v192
	s_movk_i32 s4, 0x490
	s_nop 0
	v_cmp_gt_i32_e32 vcc, s4, v168
	s_and_saveexec_b64 s[20:21], vcc
	s_cbranch_execz .LBB0_681
	v_readlane_b32 s4, v255, 11
	s_mov_b64 s[48:49], 0
	v_mov_b32_e32 v1, v168
	v_lshl_add_u32 v0, v168, 3, s4

.LBB0_722:
	s_waitcnt lgkmcnt(0)
	v_readfirstlane_b32 s2, v199
	s_cmp_eq_u32 s2, 2
	s_cbranch_scc0 .Lp3_to_att
	v_mov_b32_e32 v199, 0
	s_branch .LBB0_745
.Lp3_to_att:
	s_mov_b64 s[2:3], s[96:97]
	s_mov_b32 s4, s93
	s_mov_b32 s5, s94
	s_cmpk_gt_i32 s4, 0x1ff
	s_cbranch_scc1 .LBB0_745
	s_load_dwordx2 s[2:3], s[2:3], 0xc8
	s_waitcnt lgkmcnt(0)
	s_add_u32 s6, s2, 0x11200000
	s_addc_u32 s7, s3, 0
	s_add_u32 s8, s2, 0xd200000
	s_addc_u32 s9, s3, 0
	s_add_u32 s44, s2, 0x112d8a00
	s_addc_u32 s45, s3, 0
	s_branch .LBB0_725

.LBB0_744:
	v_mov_b32_e32 v193, 0xc1759bec
	v_mov_b32_e32 v241, 0x358637bd
	v_mov_b32_e32 v243, 0x3727c5ac
	v_mov_b32_e32 v244, 0x7f800000
	v_mov_b32_e32 v245, 0x7fc00000
	v_mov_b32_e32 v196, 0x1ff
	v_mov_b32_e32 v197, 0
	v_mov_b32_e32 v198, 0x200
	v_readlane_b32 s58, v255, 22
	v_readlane_b32 s59, v255, 23
	v_readfirstlane_b32 s2, v199
	s_cmp_eq_u32 s2, 1
	s_cbranch_scc0 .LBB0_745
	v_mov_b32_e32 v199, 2
	s_movk_i32 s8, 0x800
	s_branch .Lp3_fft_entry
